# static priority raise for the younger wave half (waves 4-7, s_setprio 1) in the attention j-loop on top of v129
# speedup vs baseline: 1.0109x; 1.0053x over previous
; __device__ __forceinline__ unsigned cvt_pk_bf16(float lo, float hi) { unsigned r; asm volatile("v_cvt_pk_bf16_f32 %0, %1, %2" : "=v"(r) : "v"(lo), "v"(hi)); return r; }
; __device__ __forceinline__ float bflo(unsigned w) { return __uint_as_float(w << 16); }
; __device__ __forceinline__ float bfhi(unsigned w) { return __uint_as_float(w & 0xffff0000u); }
; __device__ __forceinline__ float fexp2(float x) { return __builtin_amdgcn_exp2f(x); }
; __device__ __forceinline__ float half_swap_sum(float v) { const auto rr = __builtin_amdgcn_permlane32_swap(__float_as_uint(v), __float_as_uint(v), false, false); return __uint_as_float(rr[0]) + __uint_as_float(rr[1]); }
; __device__ __forceinline__ void attn_compute(Frame& F, int id) {
;     ...
;     for (int qb = 0; qb < 2; ++qb) {
;         const float mq = qb ? m1 : m0; float lt = half_swap_sum(qb ? l1 : l0); lt += fexp2(sk - mq);
;         const float inv = 1.0f / lt; const size_t tok = tok0 + 32 * qb;
; #pragma unroll
;         for (int dh = 0; dh < 2; ++dh)
; #pragma unroll
;             for (int gq = 0; gq < 4; ++gq) {
;                 const int d = 32 * dh + 8 * gq + 4 * hh;
;                 const v2u z = *(const v2u*)(ZA + tok * 512 + h * 64 + d);
;                 const f32x16& o = qb ? O1[dh] : O0[dh];
;                 v2u w; w.x = pg8::cvt_pk_bf16(o[4 * gq + 0] * inv * bflo(z.x), o[4 * gq + 1] * inv * bfhi(z.x));
;                 w.y = pg8::cvt_pk_bf16(o[4 * gq + 2] * inv * bflo(z.y), o[4 * gq + 3] * inv * bfhi(z.y));
;                 *(v2u*)(A5 + tok * 1024 + h * 64 + d) = w;
;             }
;     }
.LBB0_544:
	s_setprio 0
	s_lshl_b32 s14, s22, 1
	s_add_u32 s4, s39, s14
	s_addc_u32 s5, s40, 0
	s_add_u32 s22, s37, s14
	s_addc_u32 s23, s38, 0
	v_mov_b32_e32 v203, v2
	v_and_b32_e32 v12, 32, v0
	v_mov_b32_e32 v13, 0
	v_lshrrev_b32_e32 v12, 2, v12
	v_lshl_add_u64 v[4:5], s[4:5], 0, v[206:207]
	v_lshl_add_u64 v[4:5], v[4:5], 0, v[202:203]
	v_lshl_add_u64 v[4:5], v[4:5], 0, v[12:13]
	global_load_dwordx4 v[82:85], v[4:5], off
	global_load_dwordx4 v[86:89], v[4:5], off offset:32
	global_load_dwordx4 v[90:93], v[4:5], off offset:64
	global_load_dwordx4 v[94:97], v[4:5], off offset:96
	v_lshlrev_b64 v[10:11], 11, v[204:205]
	v_or_b32_e32 v204, 32, v204
	v_lshlrev_b64 v[8:9], 10, v[204:205]
	v_lshl_add_u64 v[8:9], s[4:5], 0, v[8:9]
	v_lshl_add_u64 v[8:9], v[8:9], 0, v[202:203]
	v_lshl_add_u64 v[8:9], v[8:9], 0, v[12:13]
	global_load_dwordx4 v[98:101], v[8:9], off
	global_load_dwordx4 v[102:105], v[8:9], off offset:32
	global_load_dwordx4 v[106:109], v[8:9], off offset:64
	global_load_dwordx4 v[110:113], v[8:9], off offset:96
	v_lshl_add_u64 v[10:11], s[22:23], 0, v[10:11]
	v_lshl_add_u64 v[10:11], v[10:11], 0, v[202:203]
	v_lshl_add_u64 v[10:11], v[10:11], 0, v[12:13]
	v_lshlrev_b64 v[16:17], 11, v[204:205]
	v_lshl_add_u64 v[16:17], s[22:23], 0, v[16:17]
	v_lshl_add_u64 v[16:17], v[16:17], 0, v[202:203]
	v_lshl_add_u64 v[16:17], v[16:17], 0, v[12:13]
	s_mov_b32 s33, s44
	v_sub_f32_e32 v8, v244, v249
	v_exp_f32_e32 v8, v8
	v_mov_b32_e32 v3, v246
	s_nop 1
	v_permlane32_swap_b32_e32 v246, v3
	v_add_f32_e32 v3, v246, v3
	v_add_f32_e32 v3, v8, v3
	v_div_scale_f32 v8, vcc, v3, v3, 1.0
	v_rcp_f32_e32 v9, v8
	v_div_scale_f32 v12, vcc, 1.0, v3, 1.0
	v_fma_f32 v13, -v8, v9, 1.0
	v_fmac_f32_e32 v9, v13, v9
	v_mul_f32_e32 v13, v12, v9
	v_fma_f32 v14, -v8, v13, v12
	v_fmac_f32_e32 v13, v14, v9
	v_fma_f32 v8, -v8, v13, v12
	v_div_fmas_f32 v8, v8, v9, v13
	v_div_fixup_f32 v3, v8, v3, 1.0
	s_waitcnt vmcnt(7)
	v_permlane32_swap_b32_e32 v82, v84
	v_permlane32_swap_b32_e32 v83, v85
	v_mul_f32_e32 v12, v66, v3
	v_mul_f32_e32 v13, v67, v3
	v_mul_f32_e32 v14, v68, v3
	v_mul_f32_e32 v15, v69, v3
	v_lshlrev_b32_e32 v4, 16, v82
	v_and_b32_e32 v5, 0xffff0000, v82
	v_lshlrev_b32_e32 v6, 16, v83
	v_and_b32_e32 v7, 0xffff0000, v83
	v_mul_f32_e32 v4, v12, v4
	v_mul_f32_e32 v5, v13, v5
	v_mul_f32_e32 v6, v14, v6
	v_mul_f32_e32 v7, v15, v7
	v_cvt_pk_bf16_f32 v82, v4, v5
	v_cvt_pk_bf16_f32 v83, v6, v7
	v_mul_f32_e32 v12, v70, v3
	v_mul_f32_e32 v13, v71, v3
	v_mul_f32_e32 v14, v72, v3
	v_mul_f32_e32 v15, v73, v3
	v_lshlrev_b32_e32 v4, 16, v84
	v_and_b32_e32 v5, 0xffff0000, v84
	v_lshlrev_b32_e32 v6, 16, v85
	v_and_b32_e32 v7, 0xffff0000, v85
	v_mul_f32_e32 v4, v12, v4
	v_mul_f32_e32 v5, v13, v5
	v_mul_f32_e32 v6, v14, v6
	v_mul_f32_e32 v7, v15, v7
	v_cvt_pk_bf16_f32 v84, v4, v5
	v_cvt_pk_bf16_f32 v85, v6, v7
	s_nop 1
	v_permlane32_swap_b32_e32 v82, v84
	v_permlane32_swap_b32_e32 v83, v85
	global_store_dwordx4 v[10:11], v[82:85], off
	s_waitcnt vmcnt(7)
	v_permlane32_swap_b32_e32 v86, v88
	v_permlane32_swap_b32_e32 v87, v89
	v_mul_f32_e32 v12, v74, v3
	v_mul_f32_e32 v13, v75, v3
	v_mul_f32_e32 v14, v76, v3
	v_mul_f32_e32 v15, v77, v3
	v_lshlrev_b32_e32 v4, 16, v86
	v_and_b32_e32 v5, 0xffff0000, v86
	v_lshlrev_b32_e32 v6, 16, v87
	v_and_b32_e32 v7, 0xffff0000, v87
	v_mul_f32_e32 v4, v12, v4
	v_mul_f32_e32 v5, v13, v5
	v_mul_f32_e32 v6, v14, v6
	v_mul_f32_e32 v7, v15, v7
	v_cvt_pk_bf16_f32 v86, v4, v5
	v_cvt_pk_bf16_f32 v87, v6, v7
	v_mul_f32_e32 v12, v78, v3
	v_mul_f32_e32 v13, v79, v3
	v_mul_f32_e32 v14, v80, v3
	v_mul_f32_e32 v15, v81, v3
	v_lshlrev_b32_e32 v4, 16, v88
	v_and_b32_e32 v5, 0xffff0000, v88
	v_lshlrev_b32_e32 v6, 16, v89
	v_and_b32_e32 v7, 0xffff0000, v89
	v_mul_f32_e32 v4, v12, v4
	v_mul_f32_e32 v5, v13, v5
	v_mul_f32_e32 v6, v14, v6
	v_mul_f32_e32 v7, v15, v7
	v_cvt_pk_bf16_f32 v88, v4, v5
	v_cvt_pk_bf16_f32 v89, v6, v7
	s_nop 1
	v_permlane32_swap_b32_e32 v86, v88
	v_permlane32_swap_b32_e32 v87, v89
	global_store_dwordx4 v[10:11], v[86:89], off offset:32
	s_waitcnt vmcnt(7)
	v_permlane32_swap_b32_e32 v90, v92
	v_permlane32_swap_b32_e32 v91, v93
	v_mul_f32_e32 v12, v50, v3
	v_mul_f32_e32 v13, v51, v3
	v_mul_f32_e32 v14, v52, v3
	v_mul_f32_e32 v15, v53, v3
	v_lshlrev_b32_e32 v4, 16, v90
	v_and_b32_e32 v5, 0xffff0000, v90
	v_lshlrev_b32_e32 v6, 16, v91
	v_and_b32_e32 v7, 0xffff0000, v91
	v_mul_f32_e32 v4, v12, v4
	v_mul_f32_e32 v5, v13, v5
	v_mul_f32_e32 v6, v14, v6
	v_mul_f32_e32 v7, v15, v7
	v_cvt_pk_bf16_f32 v90, v4, v5
	v_cvt_pk_bf16_f32 v91, v6, v7
	v_mul_f32_e32 v12, v54, v3
	v_mul_f32_e32 v13, v55, v3
	v_mul_f32_e32 v14, v56, v3
	v_mul_f32_e32 v15, v57, v3
	v_lshlrev_b32_e32 v4, 16, v92
	v_and_b32_e32 v5, 0xffff0000, v92
	v_lshlrev_b32_e32 v6, 16, v93
	v_and_b32_e32 v7, 0xffff0000, v93
	v_mul_f32_e32 v4, v12, v4
	v_mul_f32_e32 v5, v13, v5
	v_mul_f32_e32 v6, v14, v6
	v_mul_f32_e32 v7, v15, v7
	v_cvt_pk_bf16_f32 v92, v4, v5
	v_cvt_pk_bf16_f32 v93, v6, v7
	s_nop 1
	v_permlane32_swap_b32_e32 v90, v92
	v_permlane32_swap_b32_e32 v91, v93
	global_store_dwordx4 v[10:11], v[90:93], off offset:64
	s_waitcnt vmcnt(7)
; __device__ __forceinline__ unsigned cvt_pk_bf16(float lo, float hi) { unsigned r; asm volatile("v_cvt_pk_bf16_f32 %0, %1, %2" : "=v"(r) : "v"(lo), "v"(hi)); return r; }
; #define PROBE_END(id) if (PROBE_SEC == (id)) { const unsigned long long pb_t1_ = __builtin_amdgcn_s_memrealtime(), pb_dt_ = pb_t1_ - pb_t0_##id; while (__builtin_amdgcn_s_memrealtime() - pb_t1_ < pb_dt_) __builtin_amdgcn_s_sleep(4); }
; __device__ __forceinline__ float bflo(unsigned w) { return __uint_as_float(w << 16); }
; __device__ __forceinline__ float bfhi(unsigned w) { return __uint_as_float(w & 0xffff0000u); }
; __device__ __forceinline__ float fexp2(float x) { return __builtin_amdgcn_exp2f(x); }
; __device__ __forceinline__ float half_swap_sum(float v) { const auto rr = __builtin_amdgcn_permlane32_swap(__float_as_uint(v), __float_as_uint(v), false, false); return __uint_as_float(rr[0]) + __uint_as_float(rr[1]); }
; __device__ __forceinline__ void attn_compute(Frame& F, int id) {
;     ...
;     for (int qb = 0; qb < 2; ++qb) {
;         const float mq = qb ? m1 : m0; float lt = half_swap_sum(qb ? l1 : l0); lt += fexp2(sk - mq);
;         const float inv = 1.0f / lt; const size_t tok = tok0 + 32 * qb;
; #pragma unroll
;         for (int dh = 0; dh < 2; ++dh)
; #pragma unroll
;             for (int gq = 0; gq < 4; ++gq) {
;                 const int d = 32 * dh + 8 * gq + 4 * hh;
;                 const v2u z = *(const v2u*)(ZA + tok * 512 + h * 64 + d);
;                 const f32x16& o = qb ? O1[dh] : O0[dh];
;                 v2u w; w.x = pg8::cvt_pk_bf16(o[4 * gq + 0] * inv * bflo(z.x), o[4 * gq + 1] * inv * bfhi(z.x));
;                 w.y = pg8::cvt_pk_bf16(o[4 * gq + 2] * inv * bflo(z.y), o[4 * gq + 3] * inv * bfhi(z.y));
;                 *(v2u*)(A5 + tok * 1024 + h * 64 + d) = w;
;             }
;     }
;     PROBE_END(4)
;     __syncthreads();
	v_permlane32_swap_b32_e32 v94, v96
	v_permlane32_swap_b32_e32 v95, v97
	v_mul_f32_e32 v12, v58, v3
	v_mul_f32_e32 v13, v59, v3
	v_mul_f32_e32 v14, v60, v3
	v_mul_f32_e32 v15, v61, v3
	v_lshlrev_b32_e32 v4, 16, v94
	v_and_b32_e32 v5, 0xffff0000, v94
	v_lshlrev_b32_e32 v6, 16, v95
	v_and_b32_e32 v7, 0xffff0000, v95
	v_mul_f32_e32 v4, v12, v4
	v_mul_f32_e32 v5, v13, v5
	v_mul_f32_e32 v6, v14, v6
	v_mul_f32_e32 v7, v15, v7
	v_cvt_pk_bf16_f32 v94, v4, v5
	v_cvt_pk_bf16_f32 v95, v6, v7
	v_mul_f32_e32 v12, v62, v3
	v_mul_f32_e32 v13, v63, v3
	v_mul_f32_e32 v14, v64, v3
	v_mul_f32_e32 v15, v65, v3
	v_lshlrev_b32_e32 v4, 16, v96
	v_and_b32_e32 v5, 0xffff0000, v96
	v_lshlrev_b32_e32 v6, 16, v97
	v_and_b32_e32 v7, 0xffff0000, v97
	v_mul_f32_e32 v4, v12, v4
	v_mul_f32_e32 v5, v13, v5
	v_mul_f32_e32 v6, v14, v6
	v_mul_f32_e32 v7, v15, v7
	v_cvt_pk_bf16_f32 v96, v4, v5
	v_cvt_pk_bf16_f32 v97, v6, v7
	s_nop 1
	v_permlane32_swap_b32_e32 v94, v96
	v_permlane32_swap_b32_e32 v95, v97
	global_store_dwordx4 v[10:11], v[94:97], off offset:96
	v_sub_f32_e32 v8, v244, v245
	v_exp_f32_e32 v8, v8
	v_mov_b32_e32 v3, v201
	s_nop 1
	v_permlane32_swap_b32_e32 v201, v3
	v_add_f32_e32 v3, v201, v3
	v_add_f32_e32 v3, v8, v3
	v_div_scale_f32 v8, vcc, v3, v3, 1.0
	v_rcp_f32_e32 v9, v8
	v_div_scale_f32 v12, vcc, 1.0, v3, 1.0
	v_fma_f32 v13, -v8, v9, 1.0
	v_fmac_f32_e32 v9, v13, v9
	v_mul_f32_e32 v13, v12, v9
	v_fma_f32 v14, -v8, v13, v12
	v_fmac_f32_e32 v13, v14, v9
	v_fma_f32 v8, -v8, v13, v12
	v_div_fmas_f32 v8, v8, v9, v13
	v_div_fixup_f32 v3, v8, v3, 1.0
	s_waitcnt vmcnt(7)
	v_permlane32_swap_b32_e32 v98, v100
	v_permlane32_swap_b32_e32 v99, v101
	v_mul_f32_e32 v12, v34, v3
	v_mul_f32_e32 v13, v35, v3
	v_mul_f32_e32 v14, v36, v3
	v_mul_f32_e32 v15, v37, v3
	v_lshlrev_b32_e32 v4, 16, v98
	v_and_b32_e32 v5, 0xffff0000, v98
	v_lshlrev_b32_e32 v6, 16, v99
	v_and_b32_e32 v7, 0xffff0000, v99
	v_mul_f32_e32 v4, v12, v4
	v_mul_f32_e32 v5, v13, v5
	v_mul_f32_e32 v6, v14, v6
	v_mul_f32_e32 v7, v15, v7
	v_cvt_pk_bf16_f32 v98, v4, v5
	v_cvt_pk_bf16_f32 v99, v6, v7
	v_mul_f32_e32 v12, v38, v3
	v_mul_f32_e32 v13, v39, v3
	v_mul_f32_e32 v14, v40, v3
	v_mul_f32_e32 v15, v41, v3
	v_lshlrev_b32_e32 v4, 16, v100
	v_and_b32_e32 v5, 0xffff0000, v100
	v_lshlrev_b32_e32 v6, 16, v101
	v_and_b32_e32 v7, 0xffff0000, v101
	v_mul_f32_e32 v4, v12, v4
	v_mul_f32_e32 v5, v13, v5
	v_mul_f32_e32 v6, v14, v6
	v_mul_f32_e32 v7, v15, v7
	v_cvt_pk_bf16_f32 v100, v4, v5
	v_cvt_pk_bf16_f32 v101, v6, v7
	s_nop 1
	v_permlane32_swap_b32_e32 v98, v100
	v_permlane32_swap_b32_e32 v99, v101
	global_store_dwordx4 v[16:17], v[98:101], off
	s_waitcnt vmcnt(7)
	v_permlane32_swap_b32_e32 v102, v104
	v_permlane32_swap_b32_e32 v103, v105
	v_mul_f32_e32 v12, v42, v3
	v_mul_f32_e32 v13, v43, v3
	v_mul_f32_e32 v14, v44, v3
	v_mul_f32_e32 v15, v45, v3
	v_lshlrev_b32_e32 v4, 16, v102
	v_and_b32_e32 v5, 0xffff0000, v102
	v_lshlrev_b32_e32 v6, 16, v103
	v_and_b32_e32 v7, 0xffff0000, v103
	v_mul_f32_e32 v4, v12, v4
	v_mul_f32_e32 v5, v13, v5
	v_mul_f32_e32 v6, v14, v6
	v_mul_f32_e32 v7, v15, v7
	v_cvt_pk_bf16_f32 v102, v4, v5
	v_cvt_pk_bf16_f32 v103, v6, v7
	v_mul_f32_e32 v12, v46, v3
	v_mul_f32_e32 v13, v47, v3
	v_mul_f32_e32 v14, v48, v3
	v_mul_f32_e32 v15, v49, v3
	v_lshlrev_b32_e32 v4, 16, v104
	v_and_b32_e32 v5, 0xffff0000, v104
	v_lshlrev_b32_e32 v6, 16, v105
	v_and_b32_e32 v7, 0xffff0000, v105
	v_mul_f32_e32 v4, v12, v4
	v_mul_f32_e32 v5, v13, v5
	v_mul_f32_e32 v6, v14, v6
	v_mul_f32_e32 v7, v15, v7
	v_cvt_pk_bf16_f32 v104, v4, v5
	v_cvt_pk_bf16_f32 v105, v6, v7
	s_nop 1
	v_permlane32_swap_b32_e32 v102, v104
	v_permlane32_swap_b32_e32 v103, v105
	global_store_dwordx4 v[16:17], v[102:105], off offset:32
	s_waitcnt vmcnt(7)
	v_permlane32_swap_b32_e32 v106, v108
	v_permlane32_swap_b32_e32 v107, v109
	v_mul_f32_e32 v12, v18, v3
	v_mul_f32_e32 v13, v19, v3
	v_mul_f32_e32 v14, v20, v3
	v_mul_f32_e32 v15, v21, v3
	v_lshlrev_b32_e32 v4, 16, v106
	v_and_b32_e32 v5, 0xffff0000, v106
	v_lshlrev_b32_e32 v6, 16, v107
	v_and_b32_e32 v7, 0xffff0000, v107
	v_mul_f32_e32 v4, v12, v4
	v_mul_f32_e32 v5, v13, v5
	v_mul_f32_e32 v6, v14, v6
	v_mul_f32_e32 v7, v15, v7
	v_cvt_pk_bf16_f32 v106, v4, v5
	v_cvt_pk_bf16_f32 v107, v6, v7
	v_mul_f32_e32 v12, v22, v3
	v_mul_f32_e32 v13, v23, v3
	v_mul_f32_e32 v14, v24, v3
	v_mul_f32_e32 v15, v25, v3
	v_lshlrev_b32_e32 v4, 16, v108
	v_and_b32_e32 v5, 0xffff0000, v108
	v_lshlrev_b32_e32 v6, 16, v109
	v_and_b32_e32 v7, 0xffff0000, v109
	v_mul_f32_e32 v4, v12, v4
	v_mul_f32_e32 v5, v13, v5
	v_mul_f32_e32 v6, v14, v6
	v_mul_f32_e32 v7, v15, v7
	v_cvt_pk_bf16_f32 v108, v4, v5
	v_cvt_pk_bf16_f32 v109, v6, v7
	s_nop 1
	v_permlane32_swap_b32_e32 v106, v108
	v_permlane32_swap_b32_e32 v107, v109
	global_store_dwordx4 v[16:17], v[106:109], off offset:64
	s_waitcnt vmcnt(7)
	v_permlane32_swap_b32_e32 v110, v112
	v_permlane32_swap_b32_e32 v111, v113
	v_mul_f32_e32 v12, v26, v3
	v_mul_f32_e32 v13, v27, v3
	v_mul_f32_e32 v14, v28, v3
	v_mul_f32_e32 v15, v29, v3
	v_lshlrev_b32_e32 v4, 16, v110
	v_and_b32_e32 v5, 0xffff0000, v110
	v_lshlrev_b32_e32 v6, 16, v111
	v_and_b32_e32 v7, 0xffff0000, v111
	v_mul_f32_e32 v4, v12, v4
	v_mul_f32_e32 v5, v13, v5
	v_mul_f32_e32 v6, v14, v6
	v_mul_f32_e32 v7, v15, v7
	v_cvt_pk_bf16_f32 v110, v4, v5
	v_cvt_pk_bf16_f32 v111, v6, v7
	v_mul_f32_e32 v12, v30, v3
	v_mul_f32_e32 v13, v31, v3
	v_mul_f32_e32 v14, v32, v3
	v_mul_f32_e32 v15, v33, v3
	v_lshlrev_b32_e32 v4, 16, v112
	v_and_b32_e32 v5, 0xffff0000, v112
	v_lshlrev_b32_e32 v6, 16, v113
	v_and_b32_e32 v7, 0xffff0000, v113
	v_mul_f32_e32 v4, v12, v4
	v_mul_f32_e32 v5, v13, v5
	v_mul_f32_e32 v6, v14, v6
	v_mul_f32_e32 v7, v15, v7
	v_cvt_pk_bf16_f32 v112, v4, v5
	v_cvt_pk_bf16_f32 v113, v6, v7
	s_nop 1
	v_permlane32_swap_b32_e32 v110, v112
	v_permlane32_swap_b32_e32 v111, v113
	global_store_dwordx4 v[16:17], v[110:113], off offset:96
	s_andn2_b64 vcc, exec, s[2:3]
	s_barrier
	s_cbranch_vccz .LBB0_580

; #define PROBE_BEGIN(id) unsigned long long pb_t0_##id = 0; if (PROBE_SEC == (id)) pb_t0_##id = __builtin_amdgcn_s_memrealtime();
; #define LAS __attribute__((address_space(3)))
; __device__ __forceinline__ void attn_compute(Frame& F, int id) {
;     const int b = id >> 5, n = (id >> 1) & 15, kvh = id & 1;
;     LAS unsigned char* lds = F.lds;
;     const bf16* Q = (const bf16*)(F.ws + WS_Q); const bf16* ZA = (const bf16*)(F.ws + WS_ZA);
;     bf16* A5 = (bf16*)(F.ws + WS_A5);
;     const float* sink = F.in[4];
;     const int lane = F.lane, wid = F.wave;
;     const int key0 = 128 * (n - 1);
;     PROBE_BEGIN(4)
;     const int g = wid >> 1, qh = wid & 1, h = kvh * 4 + g, r = lane & 31, hh = lane >> 5;
;     const float sk = sink[h] * LOG2E;
;     const size_t tok0 = (size_t)b * SEQ + 128 * n + 64 * qh + r;
;     bf16x8 qf[2][4];
; #pragma unroll
;     for (int qb = 0; qb < 2; ++qb)
; #pragma unroll
;         for (int st = 0; st < 4; ++st) qf[qb][st] = *(const bf16x8*)(Q + (tok0 + 32 * qb) * 512 + h * 64 + 16 * st + 8 * hh);
;     const LAS f32x4* BT4 = (const LAS f32x4*)(lds + OFF_B);
;     const int ktA = 2 * qh;
;     const LAS f32x4* BTg = BT4 + g * NBT + 63 - r + 4 * hh;
;     const LAS unsigned char* kbase = lds + OFF_K + (32 * ktA + r) * KROW + 16 * hh;
;     const LAS unsigned char* vbase = lds + OFF_V + r * VROW + (32 * ktA + 4 * hh) * 2;
;     float m0 = sk, m1 = sk, l0 = 0.f, l1 = 0.f;
;     f32x16 O0[2], O1[2];
; #pragma unroll
;     for (int q = 0; q < 16; ++q) { O0[0][q] = 0.f; O0[1][q] = 0.f; O1[0][q] = 0.f; O1[1][q] = 0.f; }
; #pragma unroll 1
;     for (int j = 0; j < 9; ++j) {
.LBB0_574:
	v_readfirstlane_b32 s4, v0
	s_nop 3
	s_bitcmp1_b32 s4, 8
	s_cbranch_scc0 .Lattn_lo_half
	s_setprio 1
